# write-through (sc1) also on the 16-byte GEMM epilogue stores of P3/P5/P7/P9/P12 (DEL, in_proj, q/kv/pool outputs), on top of the LN row-store write-through
# baseline (speedup 1.0000x reference)
.LBB0_289:
	v_mov_b32_e32 v2, v184
	s_cmp_eq_u32 s93, 0
	s_nop 7
	s_nop 7
	s_nop 7
	s_cselect_b64 vcc, -1, 0
	v_add_u32_e32 v3, 0xffffe000, v2
	v_cndmask_b32_e32 v2, v3, v2, vcc
	v_lshl_add_u32 v2, s70, 8, v2
	s_and_b64 s[8:9], vcc, exec
	v_ashrrev_i32_e32 v3, 31, v2
	s_cselect_b32 s9, s21, s17
	s_cselect_b32 s8, s20, s16
	v_lshlrev_b64 v[2:3], 13, v[2:3]
	s_waitcnt vmcnt(0)
	v_pk_mul_f32 v[180:181], v[142:143], s[46:47] op_sel_hi:[1,0]
	v_lshl_add_u64 v[2:3], s[8:9], 0, v[2:3]
	v_pk_mul_f32 v[176:177], v[138:139], s[46:47] op_sel_hi:[1,0]
	v_pk_mul_f32 v[178:179], v[144:145], s[46:47] op_sel_hi:[1,0]
	v_pk_mul_f32 v[190:191], v[134:135], v[180:181]
	v_lshl_add_u64 v[6:7], v[172:173], 1, v[2:3]
	v_pk_mul_f32 v[172:173], v[150:151], s[46:47] op_sel_hi:[1,0]
	v_pk_mul_f32 v[174:175], v[140:141], s[46:47] op_sel_hi:[1,0]
	v_pk_mul_f32 v[182:183], v[136:137], v[178:179]
	v_pk_mul_f32 v[192:193], v[130:131], v[176:177]
	v_cvt_pk_bf16_f32 v190, v190, v191
	v_cvt_pk_bf16_f32 v191, v182, v183
	v_pk_mul_f32 v[4:5], v[146:147], s[46:47] op_sel_hi:[1,0]
	v_pk_mul_f32 v[8:9], v[152:153], s[46:47] op_sel_hi:[1,0]
	v_pk_mul_f32 v[194:195], v[132:133], v[174:175]
	v_cvt_pk_bf16_f32 v192, v192, v193
	v_pk_mul_f32 v[2:3], v[148:149], s[46:47] op_sel_hi:[1,0]
	v_cvt_pk_bf16_f32 v193, v194, v195
	global_store_dwordx4 v[6:7], v[190:193], off sc1
	v_pk_mul_f32 v[182:183], v[104:105], v[8:9]
	v_pk_mul_f32 v[194:195], v[100:101], v[2:3]
	v_pk_mul_f32 v[190:191], v[102:103], v[172:173]
	v_pk_mul_f32 v[192:193], v[98:99], v[4:5]
	v_cvt_pk_bf16_f32 v190, v190, v191
	v_cvt_pk_bf16_f32 v191, v182, v183
	v_pk_mul_f32 v[182:183], v[128:129], v[178:179]
	v_cvt_pk_bf16_f32 v192, v192, v193
	v_cvt_pk_bf16_f32 v193, v194, v195
	global_store_dwordx4 v[6:7], v[190:193], off offset:256 sc1
	s_mov_b32 s8, 0x20000
	v_pk_mul_f32 v[194:195], v[124:125], v[174:175]
	v_pk_mul_f32 v[190:191], v[126:127], v[180:181]
	v_pk_mul_f32 v[192:193], v[122:123], v[176:177]
	v_cvt_pk_bf16_f32 v190, v190, v191
	v_cvt_pk_bf16_f32 v191, v182, v183
	v_add_co_u32_e32 v182, vcc, s8, v6
	v_cvt_pk_bf16_f32 v192, v192, v193
	v_cvt_pk_bf16_f32 v193, v194, v195
	v_pk_mul_f32 v[194:195], v[92:93], v[2:3]
	s_nop 0
	v_addc_co_u32_e32 v183, vcc, 0, v7, vcc
	global_store_dwordx4 v[182:183], v[190:193], off sc1
	v_pk_mul_f32 v[196:197], v[90:91], v[4:5]
	s_mov_b32 s8, 0x40000
	v_pk_mul_f32 v[190:191], v[94:95], v[172:173]
	v_pk_mul_f32 v[192:193], v[96:97], v[8:9]
	v_cvt_pk_bf16_f32 v190, v190, v191
	s_nop 0
	v_cvt_pk_bf16_f32 v191, v192, v193
	v_cvt_pk_bf16_f32 v192, v196, v197
	v_cvt_pk_bf16_f32 v193, v194, v195
	global_store_dwordx4 v[182:183], v[190:193], off offset:256 sc1
	v_pk_mul_f32 v[182:183], v[120:121], v[178:179]
	v_pk_mul_f32 v[194:195], v[116:117], v[174:175]
	v_pk_mul_f32 v[190:191], v[118:119], v[180:181]
	v_pk_mul_f32 v[192:193], v[114:115], v[176:177]
	v_cvt_pk_bf16_f32 v190, v190, v191
	v_cvt_pk_bf16_f32 v191, v182, v183
	v_add_co_u32_e32 v182, vcc, s8, v6
	v_cvt_pk_bf16_f32 v192, v192, v193
	v_cvt_pk_bf16_f32 v193, v194, v195
	v_pk_mul_f32 v[194:195], v[84:85], v[2:3]
	s_nop 0
	v_addc_co_u32_e32 v183, vcc, 0, v7, vcc
	global_store_dwordx4 v[182:183], v[190:193], off sc1
	v_pk_mul_f32 v[196:197], v[82:83], v[4:5]
	s_mov_b32 s8, 0x60000
	v_pk_mul_f32 v[190:191], v[86:87], v[172:173]
	v_pk_mul_f32 v[192:193], v[88:89], v[8:9]
	v_cvt_pk_bf16_f32 v190, v190, v191
	s_nop 0
	v_cvt_pk_bf16_f32 v191, v192, v193
	v_cvt_pk_bf16_f32 v192, v196, v197
	v_cvt_pk_bf16_f32 v193, v194, v195
	global_store_dwordx4 v[182:183], v[190:193], off offset:256 sc1
	v_pk_mul_f32 v[182:183], v[112:113], v[178:179]
	v_pk_mul_f32 v[194:195], v[108:109], v[174:175]
	v_pk_mul_f32 v[190:191], v[110:111], v[180:181]
	v_pk_mul_f32 v[192:193], v[106:107], v[176:177]
	v_cvt_pk_bf16_f32 v190, v190, v191
	v_cvt_pk_bf16_f32 v191, v182, v183
	v_add_co_u32_e32 v182, vcc, s8, v6
	v_cvt_pk_bf16_f32 v192, v192, v193
	v_cvt_pk_bf16_f32 v193, v194, v195
	v_pk_mul_f32 v[194:195], v[76:77], v[2:3]
	s_nop 0
	v_addc_co_u32_e32 v183, vcc, 0, v7, vcc
	global_store_dwordx4 v[182:183], v[190:193], off sc1
	v_pk_mul_f32 v[196:197], v[74:75], v[4:5]
	s_mov_b32 s8, 0x100000
	v_pk_mul_f32 v[190:191], v[78:79], v[172:173]
	v_pk_mul_f32 v[192:193], v[80:81], v[8:9]
	v_cvt_pk_bf16_f32 v190, v190, v191
	s_nop 0
	v_cvt_pk_bf16_f32 v191, v192, v193
	v_cvt_pk_bf16_f32 v192, v196, v197
	v_cvt_pk_bf16_f32 v193, v194, v195
	global_store_dwordx4 v[182:183], v[190:193], off offset:256 sc1
	v_pk_mul_f32 v[182:183], v[72:73], v[178:179]
	v_pk_mul_f32 v[194:195], v[68:69], v[174:175]
	v_pk_mul_f32 v[190:191], v[70:71], v[180:181]
	v_pk_mul_f32 v[192:193], v[66:67], v[176:177]
	v_cvt_pk_bf16_f32 v190, v190, v191
	v_cvt_pk_bf16_f32 v191, v182, v183
	v_add_co_u32_e32 v182, vcc, s8, v6
	v_cvt_pk_bf16_f32 v192, v192, v193
	v_cvt_pk_bf16_f32 v193, v194, v195
	v_pk_mul_f32 v[194:195], v[36:37], v[2:3]
	s_nop 0
	v_addc_co_u32_e32 v183, vcc, 0, v7, vcc
	global_store_dwordx4 v[182:183], v[190:193], off sc1
	v_pk_mul_f32 v[196:197], v[34:35], v[4:5]
	s_mov_b32 s8, 0x120000
	v_pk_mul_f32 v[190:191], v[38:39], v[172:173]
	v_pk_mul_f32 v[192:193], v[40:41], v[8:9]
	v_cvt_pk_bf16_f32 v190, v190, v191
	s_nop 0
	v_cvt_pk_bf16_f32 v191, v192, v193
	v_cvt_pk_bf16_f32 v192, v196, v197
	v_cvt_pk_bf16_f32 v193, v194, v195
	global_store_dwordx4 v[182:183], v[190:193], off offset:256 sc1
	v_pk_mul_f32 v[182:183], v[64:65], v[178:179]
	v_pk_mul_f32 v[194:195], v[60:61], v[174:175]
	v_pk_mul_f32 v[190:191], v[62:63], v[180:181]
	v_pk_mul_f32 v[192:193], v[58:59], v[176:177]
	v_cvt_pk_bf16_f32 v190, v190, v191
	v_cvt_pk_bf16_f32 v191, v182, v183
	v_add_co_u32_e32 v182, vcc, s8, v6
	v_cvt_pk_bf16_f32 v192, v192, v193
	v_cvt_pk_bf16_f32 v193, v194, v195
	v_pk_mul_f32 v[194:195], v[28:29], v[2:3]
	s_nop 0
	v_addc_co_u32_e32 v183, vcc, 0, v7, vcc
	global_store_dwordx4 v[182:183], v[190:193], off sc1
	v_pk_mul_f32 v[196:197], v[26:27], v[4:5]
	s_mov_b32 s8, 0x140000
	v_pk_mul_f32 v[190:191], v[30:31], v[172:173]
	v_pk_mul_f32 v[192:193], v[32:33], v[8:9]
	v_cvt_pk_bf16_f32 v190, v190, v191
	s_nop 0
	v_cvt_pk_bf16_f32 v191, v192, v193
	v_cvt_pk_bf16_f32 v192, v196, v197
	v_cvt_pk_bf16_f32 v193, v194, v195
	global_store_dwordx4 v[182:183], v[190:193], off offset:256 sc1
	v_pk_mul_f32 v[182:183], v[56:57], v[178:179]
	v_pk_mul_f32 v[194:195], v[52:53], v[174:175]
	v_pk_mul_f32 v[190:191], v[54:55], v[180:181]
	v_pk_mul_f32 v[192:193], v[50:51], v[176:177]
	v_cvt_pk_bf16_f32 v190, v190, v191
	v_cvt_pk_bf16_f32 v191, v182, v183
	v_add_co_u32_e32 v182, vcc, s8, v6
	s_mov_b32 s8, 0x160000
	s_nop 0
	v_addc_co_u32_e32 v183, vcc, 0, v7, vcc
	v_cvt_pk_bf16_f32 v192, v192, v193
	v_cvt_pk_bf16_f32 v193, v194, v195
	v_add_co_u32_e32 v6, vcc, s8, v6
	global_store_dwordx4 v[182:183], v[190:193], off sc1
	s_nop 0
	v_addc_co_u32_e32 v7, vcc, 0, v7, vcc
	v_pk_mul_f32 v[192:193], v[24:25], v[8:9]
	v_pk_mul_f32 v[190:191], v[22:23], v[172:173]
	v_pk_mul_f32 v[194:195], v[20:21], v[2:3]
	v_pk_mul_f32 v[196:197], v[18:19], v[4:5]
	v_cvt_pk_bf16_f32 v190, v190, v191
	v_cvt_pk_bf16_f32 v191, v192, v193
	v_pk_mul_f32 v[178:179], v[48:49], v[178:179]
	v_cvt_pk_bf16_f32 v192, v196, v197
	v_cvt_pk_bf16_f32 v193, v194, v195
	global_store_dwordx4 v[182:183], v[190:193], off offset:256 sc1
	v_pk_mul_f32 v[180:181], v[46:47], v[180:181]
	v_pk_mul_f32 v[182:183], v[44:45], v[174:175]
	v_pk_mul_f32 v[176:177], v[42:43], v[176:177]
	v_cvt_pk_bf16_f32 v174, v180, v181
	v_cvt_pk_bf16_f32 v175, v178, v179
	v_pk_mul_f32 v[4:5], v[10:11], v[4:5]
	s_and_b64 vcc, exec, s[2:3]
	s_mov_b64 s[2:3], -1
	v_cvt_pk_bf16_f32 v176, v176, v177
	v_cvt_pk_bf16_f32 v177, v182, v183
	global_store_dwordx4 v[6:7], v[174:177], off sc1
	v_pk_mul_f32 v[8:9], v[16:17], v[8:9]
	v_pk_mul_f32 v[172:173], v[14:15], v[172:173]
	v_pk_mul_f32 v[174:175], v[12:13], v[2:3]
	v_cvt_pk_bf16_f32 v2, v172, v173
	v_cvt_pk_bf16_f32 v3, v8, v9
	v_cvt_pk_bf16_f32 v4, v4, v5
	s_nop 0
	v_cvt_pk_bf16_f32 v5, v174, v175
	global_store_dwordx4 v[6:7], v[2:5], off offset:256 sc1
	s_cbranch_vccnz .LBB0_269
	s_andn2_b64 vcc, exec, s[6:7]
	s_cbranch_vccnz .LBB0_268
	s_barrier
	s_branch .LBB0_268

.LBB0_441:
	v_lshl_or_b32 v4, s70, 8, v198
	v_ashrrev_i32_e32 v5, 31, v4
	v_lshl_add_u32 v16, s52, 8, v197
	v_mov_b64_e32 v[2:3], s[16:17]
	v_mad_i64_i32 v[6:7], s[8:9], v16, s95, v[2:3]
	v_lshlrev_b64 v[4:5], 1, v[4:5]
	v_lshl_add_u64 v[10:11], v[6:7], 0, v[4:5]
	v_pk_mul_f32 v[6:7], v[158:159], s[38:39] op_sel_hi:[1,0]
	s_nop 7
	s_nop 7
	s_nop 7
	v_pk_mul_f32 v[8:9], v[160:161], s[38:39] op_sel_hi:[1,0]
	v_cvt_pk_bf16_f32 v6, v6, v7
	v_pk_mul_f32 v[12:13], v[156:157], s[38:39] op_sel_hi:[1,0]
	v_cvt_pk_bf16_f32 v7, v8, v9
	v_pk_mul_f32 v[14:15], v[154:155], s[38:39] op_sel_hi:[1,0]
	s_andn2_b64 vcc, exec, s[2:3]
	v_cvt_pk_bf16_f32 v8, v14, v15
	v_cvt_pk_bf16_f32 v9, v12, v13
	global_store_dwordx4 v[10:11], v[6:9], off sc1
	v_pk_mul_f32 v[12:13], v[124:125], s[38:39] op_sel_hi:[1,0]
	v_pk_mul_f32 v[14:15], v[122:123], s[38:39] op_sel_hi:[1,0]
	v_pk_mul_f32 v[6:7], v[126:127], s[38:39] op_sel_hi:[1,0]
	v_pk_mul_f32 v[8:9], v[128:129], s[38:39] op_sel_hi:[1,0]
	v_cvt_pk_bf16_f32 v6, v6, v7
	s_mov_b64 s[2:3], -1
	v_cvt_pk_bf16_f32 v7, v8, v9
	v_cvt_pk_bf16_f32 v8, v14, v15
	v_cvt_pk_bf16_f32 v9, v12, v13
	global_store_dwordx4 v[10:11], v[6:9], off offset:256 sc1
	v_pk_mul_f32 v[12:13], v[148:149], s[38:39] op_sel_hi:[1,0]
	v_pk_mul_f32 v[14:15], v[146:147], s[38:39] op_sel_hi:[1,0]
	v_or_b32_e32 v6, 16, v16
	v_mad_i64_i32 v[6:7], s[8:9], v6, s95, v[2:3]
	v_lshl_add_u64 v[10:11], v[6:7], 0, v[4:5]
	v_pk_mul_f32 v[6:7], v[150:151], s[38:39] op_sel_hi:[1,0]
	v_pk_mul_f32 v[8:9], v[152:153], s[38:39] op_sel_hi:[1,0]
	v_cvt_pk_bf16_f32 v6, v6, v7
	s_nop 0
	v_cvt_pk_bf16_f32 v7, v8, v9
	v_cvt_pk_bf16_f32 v8, v14, v15
	v_cvt_pk_bf16_f32 v9, v12, v13
	global_store_dwordx4 v[10:11], v[6:9], off sc1
	v_pk_mul_f32 v[12:13], v[116:117], s[38:39] op_sel_hi:[1,0]
	v_pk_mul_f32 v[14:15], v[114:115], s[38:39] op_sel_hi:[1,0]
	v_pk_mul_f32 v[6:7], v[118:119], s[38:39] op_sel_hi:[1,0]
	v_pk_mul_f32 v[8:9], v[120:121], s[38:39] op_sel_hi:[1,0]
	v_cvt_pk_bf16_f32 v6, v6, v7
	s_nop 0
	v_cvt_pk_bf16_f32 v7, v8, v9
	v_cvt_pk_bf16_f32 v8, v14, v15
	v_cvt_pk_bf16_f32 v9, v12, v13
	global_store_dwordx4 v[10:11], v[6:9], off offset:256 sc1
	v_pk_mul_f32 v[12:13], v[140:141], s[38:39] op_sel_hi:[1,0]
	v_pk_mul_f32 v[14:15], v[138:139], s[38:39] op_sel_hi:[1,0]
	v_or_b32_e32 v6, 32, v16
	v_mad_i64_i32 v[6:7], s[8:9], v6, s95, v[2:3]
	v_lshl_add_u64 v[10:11], v[6:7], 0, v[4:5]
	v_pk_mul_f32 v[6:7], v[142:143], s[38:39] op_sel_hi:[1,0]
	v_pk_mul_f32 v[8:9], v[144:145], s[38:39] op_sel_hi:[1,0]
	v_cvt_pk_bf16_f32 v6, v6, v7
	s_nop 0
	v_cvt_pk_bf16_f32 v7, v8, v9
	v_cvt_pk_bf16_f32 v8, v14, v15
	v_cvt_pk_bf16_f32 v9, v12, v13
	global_store_dwordx4 v[10:11], v[6:9], off sc1
	v_pk_mul_f32 v[12:13], v[108:109], s[38:39] op_sel_hi:[1,0]
	v_pk_mul_f32 v[14:15], v[106:107], s[38:39] op_sel_hi:[1,0]
	v_pk_mul_f32 v[6:7], v[110:111], s[38:39] op_sel_hi:[1,0]
	v_pk_mul_f32 v[8:9], v[112:113], s[38:39] op_sel_hi:[1,0]
	v_cvt_pk_bf16_f32 v6, v6, v7
	s_nop 0
	v_cvt_pk_bf16_f32 v7, v8, v9
	v_cvt_pk_bf16_f32 v8, v14, v15
	v_cvt_pk_bf16_f32 v9, v12, v13
	global_store_dwordx4 v[10:11], v[6:9], off offset:256 sc1
	v_pk_mul_f32 v[12:13], v[132:133], s[38:39] op_sel_hi:[1,0]
	v_pk_mul_f32 v[14:15], v[130:131], s[38:39] op_sel_hi:[1,0]
	v_or_b32_e32 v6, 48, v16
	v_mad_i64_i32 v[6:7], s[8:9], v6, s95, v[2:3]
	v_lshl_add_u64 v[10:11], v[6:7], 0, v[4:5]
	v_pk_mul_f32 v[6:7], v[134:135], s[38:39] op_sel_hi:[1,0]
	v_pk_mul_f32 v[8:9], v[136:137], s[38:39] op_sel_hi:[1,0]
	v_cvt_pk_bf16_f32 v6, v6, v7
	s_nop 0
	v_cvt_pk_bf16_f32 v7, v8, v9
	v_cvt_pk_bf16_f32 v8, v14, v15
	v_cvt_pk_bf16_f32 v9, v12, v13
	global_store_dwordx4 v[10:11], v[6:9], off sc1
	v_pk_mul_f32 v[12:13], v[100:101], s[38:39] op_sel_hi:[1,0]
	v_pk_mul_f32 v[14:15], v[98:99], s[38:39] op_sel_hi:[1,0]
	v_pk_mul_f32 v[6:7], v[102:103], s[38:39] op_sel_hi:[1,0]
	v_pk_mul_f32 v[8:9], v[104:105], s[38:39] op_sel_hi:[1,0]
	v_cvt_pk_bf16_f32 v6, v6, v7
	s_nop 0
	v_cvt_pk_bf16_f32 v7, v8, v9
	v_cvt_pk_bf16_f32 v8, v14, v15
	v_cvt_pk_bf16_f32 v9, v12, v13
	global_store_dwordx4 v[10:11], v[6:9], off offset:256 sc1
	v_pk_mul_f32 v[12:13], v[92:93], s[38:39] op_sel_hi:[1,0]
	v_pk_mul_f32 v[14:15], v[90:91], s[38:39] op_sel_hi:[1,0]
	v_add_u32_e32 v6, 0x80, v16
	v_mad_i64_i32 v[6:7], s[8:9], v6, s95, v[2:3]
	v_lshl_add_u64 v[10:11], v[6:7], 0, v[4:5]
	v_pk_mul_f32 v[6:7], v[94:95], s[38:39] op_sel_hi:[1,0]
	v_pk_mul_f32 v[8:9], v[96:97], s[38:39] op_sel_hi:[1,0]
	v_cvt_pk_bf16_f32 v6, v6, v7
	s_nop 0
	v_cvt_pk_bf16_f32 v7, v8, v9
	v_cvt_pk_bf16_f32 v8, v14, v15
	v_cvt_pk_bf16_f32 v9, v12, v13
	global_store_dwordx4 v[10:11], v[6:9], off sc1
	v_pk_mul_f32 v[12:13], v[60:61], s[38:39] op_sel_hi:[1,0]
	v_pk_mul_f32 v[14:15], v[58:59], s[38:39] op_sel_hi:[1,0]
	v_pk_mul_f32 v[6:7], v[62:63], s[38:39] op_sel_hi:[1,0]
	v_pk_mul_f32 v[8:9], v[64:65], s[38:39] op_sel_hi:[1,0]
	v_cvt_pk_bf16_f32 v6, v6, v7
	s_nop 0
	v_cvt_pk_bf16_f32 v7, v8, v9
	v_cvt_pk_bf16_f32 v8, v14, v15
	v_cvt_pk_bf16_f32 v9, v12, v13
	global_store_dwordx4 v[10:11], v[6:9], off offset:256 sc1
	v_pk_mul_f32 v[12:13], v[84:85], s[38:39] op_sel_hi:[1,0]
	v_pk_mul_f32 v[14:15], v[82:83], s[38:39] op_sel_hi:[1,0]
	v_add_u32_e32 v6, 0x90, v16
	v_mad_i64_i32 v[6:7], s[8:9], v6, s95, v[2:3]
	v_lshl_add_u64 v[10:11], v[6:7], 0, v[4:5]
	v_pk_mul_f32 v[6:7], v[86:87], s[38:39] op_sel_hi:[1,0]
	v_pk_mul_f32 v[8:9], v[88:89], s[38:39] op_sel_hi:[1,0]
	v_cvt_pk_bf16_f32 v6, v6, v7
	s_nop 0
	v_cvt_pk_bf16_f32 v7, v8, v9
	v_cvt_pk_bf16_f32 v8, v14, v15
	v_cvt_pk_bf16_f32 v9, v12, v13
	global_store_dwordx4 v[10:11], v[6:9], off sc1
	v_pk_mul_f32 v[12:13], v[52:53], s[38:39] op_sel_hi:[1,0]
	v_pk_mul_f32 v[14:15], v[50:51], s[38:39] op_sel_hi:[1,0]
	v_pk_mul_f32 v[6:7], v[54:55], s[38:39] op_sel_hi:[1,0]
	v_pk_mul_f32 v[8:9], v[56:57], s[38:39] op_sel_hi:[1,0]
	v_cvt_pk_bf16_f32 v6, v6, v7
	s_nop 0
	v_cvt_pk_bf16_f32 v7, v8, v9
	v_cvt_pk_bf16_f32 v8, v14, v15
	v_cvt_pk_bf16_f32 v9, v12, v13
	global_store_dwordx4 v[10:11], v[6:9], off offset:256 sc1
	v_pk_mul_f32 v[12:13], v[76:77], s[38:39] op_sel_hi:[1,0]
	v_pk_mul_f32 v[14:15], v[74:75], s[38:39] op_sel_hi:[1,0]
	v_add_u32_e32 v6, 0xa0, v16
	v_mad_i64_i32 v[6:7], s[8:9], v6, s95, v[2:3]
	v_lshl_add_u64 v[10:11], v[6:7], 0, v[4:5]
	v_pk_mul_f32 v[6:7], v[78:79], s[38:39] op_sel_hi:[1,0]
	v_pk_mul_f32 v[8:9], v[80:81], s[38:39] op_sel_hi:[1,0]
	v_cvt_pk_bf16_f32 v6, v6, v7
	s_nop 0
	v_cvt_pk_bf16_f32 v7, v8, v9
	v_cvt_pk_bf16_f32 v8, v14, v15
	v_cvt_pk_bf16_f32 v9, v12, v13
	global_store_dwordx4 v[10:11], v[6:9], off sc1
	v_pk_mul_f32 v[12:13], v[44:45], s[38:39] op_sel_hi:[1,0]
	v_pk_mul_f32 v[14:15], v[42:43], s[38:39] op_sel_hi:[1,0]
	v_pk_mul_f32 v[6:7], v[46:47], s[38:39] op_sel_hi:[1,0]
	v_pk_mul_f32 v[8:9], v[48:49], s[38:39] op_sel_hi:[1,0]
	v_cvt_pk_bf16_f32 v6, v6, v7
	s_nop 0
	v_cvt_pk_bf16_f32 v7, v8, v9
	v_cvt_pk_bf16_f32 v8, v14, v15
	v_cvt_pk_bf16_f32 v9, v12, v13
	global_store_dwordx4 v[10:11], v[6:9], off offset:256 sc1
	v_pk_mul_f32 v[10:11], v[66:67], s[38:39] op_sel_hi:[1,0]
	s_nop 0
	v_add_u32_e32 v6, 0xb0, v16
	v_mad_i64_i32 v[2:3], s[8:9], v6, s95, v[2:3]
	v_lshl_add_u64 v[6:7], v[2:3], 0, v[4:5]
	v_pk_mul_f32 v[4:5], v[72:73], s[38:39] op_sel_hi:[1,0]
	v_pk_mul_f32 v[2:3], v[70:71], s[38:39] op_sel_hi:[1,0]
	v_pk_mul_f32 v[8:9], v[68:69], s[38:39] op_sel_hi:[1,0]
	v_cvt_pk_bf16_f32 v2, v2, v3
	v_cvt_pk_bf16_f32 v3, v4, v5
	v_cvt_pk_bf16_f32 v4, v10, v11
	v_pk_mul_f32 v[10:11], v[34:35], s[38:39] op_sel_hi:[1,0]
	v_cvt_pk_bf16_f32 v5, v8, v9
	global_store_dwordx4 v[6:7], v[2:5], off sc1
	v_pk_mul_f32 v[8:9], v[36:37], s[38:39] op_sel_hi:[1,0]
	s_nop 0
	v_pk_mul_f32 v[4:5], v[40:41], s[38:39] op_sel_hi:[1,0]
	v_pk_mul_f32 v[2:3], v[38:39], s[38:39] op_sel_hi:[1,0]
	s_nop 0
	v_cvt_pk_bf16_f32 v2, v2, v3
	v_cvt_pk_bf16_f32 v3, v4, v5
	v_cvt_pk_bf16_f32 v4, v10, v11
	v_cvt_pk_bf16_f32 v5, v8, v9
	global_store_dwordx4 v[6:7], v[2:5], off offset:256 sc1
	s_cbranch_vccnz .LBB0_434
	s_andn2_b64 vcc, exec, s[0:1]
	s_cbranch_vccnz .LBB0_433
	s_barrier
	s_branch .LBB0_433

.LBB0_458:
	global_store_dwordx4 v[140:141], v[126:129], off sc1
	global_store_dwordx4 v[140:141], v[122:125], off offset:64 sc1
	s_nop 1
	v_add_co_u32_e32 v122, vcc, 0xc000, v140
	s_nop 1
	v_addc_co_u32_e32 v123, vcc, 0, v141, vcc
	global_store_dwordx4 v[122:123], v[118:121], off sc1
	global_store_dwordx4 v[122:123], v[114:117], off offset:64 sc1
	s_nop 1
	v_add_co_u32_e32 v114, vcc, 0x18000, v140
	s_nop 1
	v_addc_co_u32_e32 v115, vcc, 0, v141, vcc
	global_store_dwordx4 v[114:115], v[110:113], off sc1
	global_store_dwordx4 v[114:115], v[106:109], off offset:64 sc1
	s_nop 1
	v_add_co_u32_e32 v106, vcc, 0x24000, v140
	s_nop 1
	v_addc_co_u32_e32 v107, vcc, 0, v141, vcc
	global_store_dwordx4 v[106:107], v[102:105], off sc1
	global_store_dwordx4 v[106:107], v[98:101], off offset:64 sc1
	s_nop 1
	v_add_co_u32_e32 v98, vcc, 0x60000, v140
	s_nop 1
	v_addc_co_u32_e32 v99, vcc, 0, v141, vcc
	global_store_dwordx4 v[98:99], v[94:97], off sc1
	global_store_dwordx4 v[98:99], v[86:89], off offset:64 sc1
	s_nop 1
	v_add_co_u32_e32 v86, vcc, 0x6c000, v140
	s_nop 1
	v_addc_co_u32_e32 v87, vcc, 0, v141, vcc
	global_store_dwordx4 v[86:87], v[78:81], off sc1
	global_store_dwordx4 v[86:87], v[70:73], off offset:64 sc1
	s_nop 1
	v_add_co_u32_e32 v70, vcc, 0x78000, v140
	s_nop 1
	v_addc_co_u32_e32 v71, vcc, 0, v141, vcc
	global_store_dwordx4 v[70:71], v[62:65], off sc1
	global_store_dwordx4 v[70:71], v[54:57], off offset:64 sc1
	s_nop 1
	v_add_co_u32_e32 v54, vcc, 0x84000, v140
	s_nop 1
	v_addc_co_u32_e32 v55, vcc, 0, v141, vcc
	global_store_dwordx4 v[54:55], v[46:49], off sc1
	global_store_dwordx4 v[54:55], v[38:41], off offset:64 sc1
	s_or_b32 s8, s44, 0x80
	s_cmpk_gt_i32 s8, 0x23f
	s_cbranch_scc1 .LBB0_457
.LBB0_459:
	v_add_co_u32_e32 v38, vcc, 0xc000, v140
	global_store_dwordx4 v[140:141], v[90:93], off offset:512 sc1
	global_store_dwordx4 v[140:141], v[82:85], off offset:576 sc1
	v_addc_co_u32_e32 v39, vcc, 0, v141, vcc
	global_store_dwordx4 v[38:39], v[74:77], off offset:512 sc1
	global_store_dwordx4 v[38:39], v[66:69], off offset:576 sc1
	v_add_co_u32_e32 v38, vcc, 0x18000, v140
	s_nop 1
	v_addc_co_u32_e32 v39, vcc, 0, v141, vcc
	global_store_dwordx4 v[38:39], v[58:61], off offset:512 sc1
	global_store_dwordx4 v[38:39], v[50:53], off offset:576 sc1
	v_add_co_u32_e32 v38, vcc, 0x24000, v140
	s_nop 1
	v_addc_co_u32_e32 v39, vcc, 0, v141, vcc
	global_store_dwordx4 v[38:39], v[42:45], off offset:512 sc1
	global_store_dwordx4 v[38:39], v[34:37], off offset:576 sc1
	s_nop 1
	v_add_co_u32_e32 v34, vcc, 0x60000, v140
	s_nop 1
	v_addc_co_u32_e32 v35, vcc, 0, v141, vcc
	global_store_dwordx4 v[34:35], v[30:33], off offset:512 sc1
	global_store_dwordx4 v[34:35], v[26:29], off offset:576 sc1
	s_nop 1
	v_add_co_u32_e32 v26, vcc, 0x6c000, v140
	s_nop 1
	v_addc_co_u32_e32 v27, vcc, 0, v141, vcc
	global_store_dwordx4 v[26:27], v[22:25], off offset:512 sc1
	global_store_dwordx4 v[26:27], v[18:21], off offset:576 sc1
	s_nop 1
	v_add_co_u32_e32 v18, vcc, 0x78000, v140
	s_nop 1
	v_addc_co_u32_e32 v19, vcc, 0, v141, vcc
	global_store_dwordx4 v[18:19], v[14:17], off offset:512 sc1
	global_store_dwordx4 v[18:19], v[10:13], off offset:576 sc1
	s_nop 1
	v_add_co_u32_e32 v10, vcc, 0x84000, v140
	s_nop 1
	v_addc_co_u32_e32 v11, vcc, 0, v141, vcc
	global_store_dwordx4 v[10:11], v[6:9], off offset:512 sc1
	global_store_dwordx4 v[10:11], v[2:5], off offset:576 sc1
	s_and_b64 vcc, exec, s[2:3]
	s_mov_b64 s[2:3], -1
	s_cbranch_vccnz .LBB0_450

.LBB0_604:
	v_lshl_or_b32 v4, s70, 8, v198
	v_ashrrev_i32_e32 v5, 31, v4
	v_lshl_add_u32 v16, s76, 8, v197
	v_mov_b64_e32 v[2:3], s[18:19]
	v_mad_i64_i32 v[6:7], s[4:5], v16, s97, v[2:3]
	v_lshlrev_b64 v[4:5], 1, v[4:5]
	v_lshl_add_u64 v[10:11], v[6:7], 0, v[4:5]
	v_pk_mul_f32 v[6:7], v[158:159], s[50:51] op_sel_hi:[1,0]
	s_nop 7
	s_nop 7
	s_nop 7
	v_pk_mul_f32 v[8:9], v[160:161], s[50:51] op_sel_hi:[1,0]
	v_cvt_pk_bf16_f32 v6, v6, v7
	v_pk_mul_f32 v[12:13], v[156:157], s[50:51] op_sel_hi:[1,0]
	v_cvt_pk_bf16_f32 v7, v8, v9
	v_pk_mul_f32 v[14:15], v[154:155], s[50:51] op_sel_hi:[1,0]
	s_andn2_b64 vcc, exec, s[2:3]
	v_cvt_pk_bf16_f32 v8, v14, v15
	v_cvt_pk_bf16_f32 v9, v12, v13
	global_store_dwordx4 v[10:11], v[6:9], off sc1
	v_pk_mul_f32 v[12:13], v[124:125], s[50:51] op_sel_hi:[1,0]
	v_pk_mul_f32 v[14:15], v[122:123], s[50:51] op_sel_hi:[1,0]
	v_pk_mul_f32 v[6:7], v[126:127], s[50:51] op_sel_hi:[1,0]
	v_pk_mul_f32 v[8:9], v[128:129], s[50:51] op_sel_hi:[1,0]
	v_cvt_pk_bf16_f32 v6, v6, v7
	s_mov_b64 s[2:3], -1
	v_cvt_pk_bf16_f32 v7, v8, v9
	v_cvt_pk_bf16_f32 v8, v14, v15
	v_cvt_pk_bf16_f32 v9, v12, v13
	global_store_dwordx4 v[10:11], v[6:9], off offset:256 sc1
	v_pk_mul_f32 v[12:13], v[148:149], s[50:51] op_sel_hi:[1,0]
	v_pk_mul_f32 v[14:15], v[146:147], s[50:51] op_sel_hi:[1,0]
	v_or_b32_e32 v6, 16, v16
	v_mad_i64_i32 v[6:7], s[4:5], v6, s97, v[2:3]
	v_lshl_add_u64 v[10:11], v[6:7], 0, v[4:5]
	v_pk_mul_f32 v[6:7], v[150:151], s[50:51] op_sel_hi:[1,0]
	v_pk_mul_f32 v[8:9], v[152:153], s[50:51] op_sel_hi:[1,0]
	v_cvt_pk_bf16_f32 v6, v6, v7
	s_nop 0
	v_cvt_pk_bf16_f32 v7, v8, v9
	v_cvt_pk_bf16_f32 v8, v14, v15
	v_cvt_pk_bf16_f32 v9, v12, v13
	global_store_dwordx4 v[10:11], v[6:9], off sc1
	v_pk_mul_f32 v[12:13], v[116:117], s[50:51] op_sel_hi:[1,0]
	v_pk_mul_f32 v[14:15], v[114:115], s[50:51] op_sel_hi:[1,0]
	v_pk_mul_f32 v[6:7], v[118:119], s[50:51] op_sel_hi:[1,0]
	v_pk_mul_f32 v[8:9], v[120:121], s[50:51] op_sel_hi:[1,0]
	v_cvt_pk_bf16_f32 v6, v6, v7
	s_nop 0
	v_cvt_pk_bf16_f32 v7, v8, v9
	v_cvt_pk_bf16_f32 v8, v14, v15
	v_cvt_pk_bf16_f32 v9, v12, v13
	global_store_dwordx4 v[10:11], v[6:9], off offset:256 sc1
	v_pk_mul_f32 v[12:13], v[140:141], s[50:51] op_sel_hi:[1,0]
	v_pk_mul_f32 v[14:15], v[138:139], s[50:51] op_sel_hi:[1,0]
	v_or_b32_e32 v6, 32, v16
	v_mad_i64_i32 v[6:7], s[4:5], v6, s97, v[2:3]
	v_lshl_add_u64 v[10:11], v[6:7], 0, v[4:5]
	v_pk_mul_f32 v[6:7], v[142:143], s[50:51] op_sel_hi:[1,0]
	v_pk_mul_f32 v[8:9], v[144:145], s[50:51] op_sel_hi:[1,0]
	v_cvt_pk_bf16_f32 v6, v6, v7
	s_nop 0
	v_cvt_pk_bf16_f32 v7, v8, v9
	v_cvt_pk_bf16_f32 v8, v14, v15
	v_cvt_pk_bf16_f32 v9, v12, v13
	global_store_dwordx4 v[10:11], v[6:9], off sc1
	v_pk_mul_f32 v[12:13], v[108:109], s[50:51] op_sel_hi:[1,0]
	v_pk_mul_f32 v[14:15], v[106:107], s[50:51] op_sel_hi:[1,0]
	v_pk_mul_f32 v[6:7], v[110:111], s[50:51] op_sel_hi:[1,0]
	v_pk_mul_f32 v[8:9], v[112:113], s[50:51] op_sel_hi:[1,0]
	v_cvt_pk_bf16_f32 v6, v6, v7
	s_nop 0
	v_cvt_pk_bf16_f32 v7, v8, v9
	v_cvt_pk_bf16_f32 v8, v14, v15
	v_cvt_pk_bf16_f32 v9, v12, v13
	global_store_dwordx4 v[10:11], v[6:9], off offset:256 sc1
	v_pk_mul_f32 v[12:13], v[132:133], s[50:51] op_sel_hi:[1,0]
	v_pk_mul_f32 v[14:15], v[130:131], s[50:51] op_sel_hi:[1,0]
	v_or_b32_e32 v6, 48, v16
	v_mad_i64_i32 v[6:7], s[4:5], v6, s97, v[2:3]
	v_lshl_add_u64 v[10:11], v[6:7], 0, v[4:5]
	v_pk_mul_f32 v[6:7], v[134:135], s[50:51] op_sel_hi:[1,0]
	v_pk_mul_f32 v[8:9], v[136:137], s[50:51] op_sel_hi:[1,0]
	v_cvt_pk_bf16_f32 v6, v6, v7
	s_nop 0
	v_cvt_pk_bf16_f32 v7, v8, v9
	v_cvt_pk_bf16_f32 v8, v14, v15
	v_cvt_pk_bf16_f32 v9, v12, v13
	global_store_dwordx4 v[10:11], v[6:9], off sc1
	v_pk_mul_f32 v[12:13], v[100:101], s[50:51] op_sel_hi:[1,0]
	v_pk_mul_f32 v[14:15], v[98:99], s[50:51] op_sel_hi:[1,0]
	v_pk_mul_f32 v[6:7], v[102:103], s[50:51] op_sel_hi:[1,0]
	v_pk_mul_f32 v[8:9], v[104:105], s[50:51] op_sel_hi:[1,0]
	v_cvt_pk_bf16_f32 v6, v6, v7
	s_nop 0
	v_cvt_pk_bf16_f32 v7, v8, v9
	v_cvt_pk_bf16_f32 v8, v14, v15
	v_cvt_pk_bf16_f32 v9, v12, v13
	global_store_dwordx4 v[10:11], v[6:9], off offset:256 sc1
	v_pk_mul_f32 v[12:13], v[92:93], s[50:51] op_sel_hi:[1,0]
	v_pk_mul_f32 v[14:15], v[90:91], s[50:51] op_sel_hi:[1,0]
	v_add_u32_e32 v6, 0x80, v16
	v_mad_i64_i32 v[6:7], s[4:5], v6, s97, v[2:3]
	v_lshl_add_u64 v[10:11], v[6:7], 0, v[4:5]
	v_pk_mul_f32 v[6:7], v[94:95], s[50:51] op_sel_hi:[1,0]
	v_pk_mul_f32 v[8:9], v[96:97], s[50:51] op_sel_hi:[1,0]
	v_cvt_pk_bf16_f32 v6, v6, v7
	s_nop 0
	v_cvt_pk_bf16_f32 v7, v8, v9
	v_cvt_pk_bf16_f32 v8, v14, v15
	v_cvt_pk_bf16_f32 v9, v12, v13
	global_store_dwordx4 v[10:11], v[6:9], off sc1
	v_pk_mul_f32 v[12:13], v[60:61], s[50:51] op_sel_hi:[1,0]
	v_pk_mul_f32 v[14:15], v[58:59], s[50:51] op_sel_hi:[1,0]
	v_pk_mul_f32 v[6:7], v[62:63], s[50:51] op_sel_hi:[1,0]
	v_pk_mul_f32 v[8:9], v[64:65], s[50:51] op_sel_hi:[1,0]
	v_cvt_pk_bf16_f32 v6, v6, v7
	s_nop 0
	v_cvt_pk_bf16_f32 v7, v8, v9
	v_cvt_pk_bf16_f32 v8, v14, v15
	v_cvt_pk_bf16_f32 v9, v12, v13
	global_store_dwordx4 v[10:11], v[6:9], off offset:256 sc1
	v_pk_mul_f32 v[12:13], v[84:85], s[50:51] op_sel_hi:[1,0]
	v_pk_mul_f32 v[14:15], v[82:83], s[50:51] op_sel_hi:[1,0]
	v_add_u32_e32 v6, 0x90, v16
	v_mad_i64_i32 v[6:7], s[4:5], v6, s97, v[2:3]
	v_lshl_add_u64 v[10:11], v[6:7], 0, v[4:5]
	v_pk_mul_f32 v[6:7], v[86:87], s[50:51] op_sel_hi:[1,0]
	v_pk_mul_f32 v[8:9], v[88:89], s[50:51] op_sel_hi:[1,0]
	v_cvt_pk_bf16_f32 v6, v6, v7
	s_nop 0
	v_cvt_pk_bf16_f32 v7, v8, v9
	v_cvt_pk_bf16_f32 v8, v14, v15
	v_cvt_pk_bf16_f32 v9, v12, v13
	global_store_dwordx4 v[10:11], v[6:9], off sc1
	v_pk_mul_f32 v[12:13], v[52:53], s[50:51] op_sel_hi:[1,0]
	v_pk_mul_f32 v[14:15], v[50:51], s[50:51] op_sel_hi:[1,0]
	v_pk_mul_f32 v[6:7], v[54:55], s[50:51] op_sel_hi:[1,0]
	v_pk_mul_f32 v[8:9], v[56:57], s[50:51] op_sel_hi:[1,0]
	v_cvt_pk_bf16_f32 v6, v6, v7
	s_nop 0
	v_cvt_pk_bf16_f32 v7, v8, v9
	v_cvt_pk_bf16_f32 v8, v14, v15
	v_cvt_pk_bf16_f32 v9, v12, v13
	global_store_dwordx4 v[10:11], v[6:9], off offset:256 sc1
	v_pk_mul_f32 v[12:13], v[76:77], s[50:51] op_sel_hi:[1,0]
	v_pk_mul_f32 v[14:15], v[74:75], s[50:51] op_sel_hi:[1,0]
	v_add_u32_e32 v6, 0xa0, v16
	v_mad_i64_i32 v[6:7], s[4:5], v6, s97, v[2:3]
	v_lshl_add_u64 v[10:11], v[6:7], 0, v[4:5]
	v_pk_mul_f32 v[6:7], v[78:79], s[50:51] op_sel_hi:[1,0]
	v_pk_mul_f32 v[8:9], v[80:81], s[50:51] op_sel_hi:[1,0]
	v_cvt_pk_bf16_f32 v6, v6, v7
	s_nop 0
	v_cvt_pk_bf16_f32 v7, v8, v9
	v_cvt_pk_bf16_f32 v8, v14, v15
	v_cvt_pk_bf16_f32 v9, v12, v13
	global_store_dwordx4 v[10:11], v[6:9], off sc1
	v_pk_mul_f32 v[12:13], v[44:45], s[50:51] op_sel_hi:[1,0]
	v_pk_mul_f32 v[14:15], v[42:43], s[50:51] op_sel_hi:[1,0]
	v_pk_mul_f32 v[6:7], v[46:47], s[50:51] op_sel_hi:[1,0]
	v_pk_mul_f32 v[8:9], v[48:49], s[50:51] op_sel_hi:[1,0]
	v_cvt_pk_bf16_f32 v6, v6, v7
	s_nop 0
	v_cvt_pk_bf16_f32 v7, v8, v9
	v_cvt_pk_bf16_f32 v8, v14, v15
	v_cvt_pk_bf16_f32 v9, v12, v13
	global_store_dwordx4 v[10:11], v[6:9], off offset:256 sc1
	v_pk_mul_f32 v[10:11], v[66:67], s[50:51] op_sel_hi:[1,0]
	s_nop 0
	v_add_u32_e32 v6, 0xb0, v16
	v_mad_i64_i32 v[2:3], s[4:5], v6, s97, v[2:3]
	v_lshl_add_u64 v[6:7], v[2:3], 0, v[4:5]
	v_pk_mul_f32 v[4:5], v[72:73], s[50:51] op_sel_hi:[1,0]
	v_pk_mul_f32 v[2:3], v[70:71], s[50:51] op_sel_hi:[1,0]
	v_pk_mul_f32 v[8:9], v[68:69], s[50:51] op_sel_hi:[1,0]
	v_cvt_pk_bf16_f32 v2, v2, v3
	v_cvt_pk_bf16_f32 v3, v4, v5
	v_cvt_pk_bf16_f32 v4, v10, v11
	v_pk_mul_f32 v[10:11], v[34:35], s[50:51] op_sel_hi:[1,0]
	v_cvt_pk_bf16_f32 v5, v8, v9
	global_store_dwordx4 v[6:7], v[2:5], off sc1
	v_pk_mul_f32 v[8:9], v[36:37], s[50:51] op_sel_hi:[1,0]
	s_nop 0
	v_pk_mul_f32 v[4:5], v[40:41], s[50:51] op_sel_hi:[1,0]
	v_pk_mul_f32 v[2:3], v[38:39], s[50:51] op_sel_hi:[1,0]
	s_nop 0
	v_cvt_pk_bf16_f32 v2, v2, v3
	v_cvt_pk_bf16_f32 v3, v4, v5
	v_cvt_pk_bf16_f32 v4, v10, v11
	v_cvt_pk_bf16_f32 v5, v8, v9
	global_store_dwordx4 v[6:7], v[2:5], off offset:256 sc1
	s_cbranch_vccnz .LBB0_597
	s_andn2_b64 vcc, exec, s[40:41]
	s_cbranch_vccnz .LBB0_596
	s_barrier
	s_branch .LBB0_596

.LBB0_618:
	v_lshl_add_u32 v8, s76, 8, v186
	v_lshl_or_b32 v2, s4, 8, v187
	v_ashrrev_i32_e32 v9, 31, v8
	v_ashrrev_i32_e32 v3, 31, v2
	v_lshlrev_b64 v[4:5], 13, v[8:9]
	v_lshl_add_u64 v[4:5], s[0:1], 0, v[4:5]
	v_lshlrev_b64 v[10:11], 1, v[2:3]
	v_lshl_add_u64 v[2:3], v[4:5], 0, v[10:11]
	v_pk_mul_f32 v[4:5], v[158:159], s[50:51] op_sel_hi:[1,0]
	s_nop 7
	s_nop 7
	s_nop 7
	v_pk_mul_f32 v[6:7], v[160:161], s[50:51] op_sel_hi:[1,0]
	v_cvt_pk_bf16_f32 v4, v4, v5
	v_pk_mul_f32 v[12:13], v[156:157], s[50:51] op_sel_hi:[1,0]
	v_cvt_pk_bf16_f32 v5, v6, v7
	v_pk_mul_f32 v[14:15], v[154:155], s[50:51] op_sel_hi:[1,0]
	v_pk_mul_f32 v[16:17], v[146:147], s[50:51] op_sel_hi:[1,0]
	v_cvt_pk_bf16_f32 v6, v14, v15
	v_cvt_pk_bf16_f32 v7, v12, v13
	global_store_dwordx4 v[2:3], v[4:7], off sc1
	v_pk_mul_f32 v[12:13], v[124:125], s[50:51] op_sel_hi:[1,0]
	v_pk_mul_f32 v[14:15], v[122:123], s[50:51] op_sel_hi:[1,0]
	v_pk_mul_f32 v[4:5], v[126:127], s[50:51] op_sel_hi:[1,0]
	v_pk_mul_f32 v[6:7], v[128:129], s[50:51] op_sel_hi:[1,0]
	v_cvt_pk_bf16_f32 v4, v4, v5
	s_mov_b64 s[4:5], 0x100000
	v_cvt_pk_bf16_f32 v5, v6, v7
	v_cvt_pk_bf16_f32 v6, v14, v15
	v_cvt_pk_bf16_f32 v7, v12, v13
	global_store_dwordx4 v[2:3], v[4:7], off offset:256 sc1
	v_pk_mul_f32 v[14:15], v[148:149], s[50:51] op_sel_hi:[1,0]
	s_nop 0
	v_or_b32_e32 v4, 16, v8
	v_ashrrev_i32_e32 v5, 31, v4
	v_lshlrev_b64 v[4:5], 13, v[4:5]
	v_lshl_add_u64 v[4:5], s[0:1], 0, v[4:5]
	v_lshl_add_u64 v[12:13], v[4:5], 0, v[10:11]
	v_pk_mul_f32 v[4:5], v[150:151], s[50:51] op_sel_hi:[1,0]
	v_pk_mul_f32 v[6:7], v[152:153], s[50:51] op_sel_hi:[1,0]
	v_cvt_pk_bf16_f32 v4, v4, v5
	s_nop 0
	v_cvt_pk_bf16_f32 v5, v6, v7
	v_cvt_pk_bf16_f32 v6, v16, v17
	v_cvt_pk_bf16_f32 v7, v14, v15
	global_store_dwordx4 v[12:13], v[4:7], off sc1
	v_pk_mul_f32 v[14:15], v[116:117], s[50:51] op_sel_hi:[1,0]
	v_pk_mul_f32 v[16:17], v[114:115], s[50:51] op_sel_hi:[1,0]
	v_pk_mul_f32 v[4:5], v[118:119], s[50:51] op_sel_hi:[1,0]
	v_pk_mul_f32 v[6:7], v[120:121], s[50:51] op_sel_hi:[1,0]
	v_cvt_pk_bf16_f32 v4, v4, v5
	s_nop 0
	v_cvt_pk_bf16_f32 v5, v6, v7
	v_cvt_pk_bf16_f32 v6, v16, v17
	v_cvt_pk_bf16_f32 v7, v14, v15
	global_store_dwordx4 v[12:13], v[4:7], off offset:256 sc1
	v_pk_mul_f32 v[14:15], v[140:141], s[50:51] op_sel_hi:[1,0]
	v_pk_mul_f32 v[16:17], v[138:139], s[50:51] op_sel_hi:[1,0]
	v_or_b32_e32 v4, 32, v8
	v_ashrrev_i32_e32 v5, 31, v4
	v_lshlrev_b64 v[4:5], 13, v[4:5]
	v_lshl_add_u64 v[4:5], s[0:1], 0, v[4:5]
	v_lshl_add_u64 v[12:13], v[4:5], 0, v[10:11]
	v_pk_mul_f32 v[4:5], v[142:143], s[50:51] op_sel_hi:[1,0]
	v_pk_mul_f32 v[6:7], v[144:145], s[50:51] op_sel_hi:[1,0]
	v_cvt_pk_bf16_f32 v4, v4, v5
	s_nop 0
	v_cvt_pk_bf16_f32 v5, v6, v7
	v_cvt_pk_bf16_f32 v6, v16, v17
	v_cvt_pk_bf16_f32 v7, v14, v15
	global_store_dwordx4 v[12:13], v[4:7], off sc1
	v_pk_mul_f32 v[14:15], v[108:109], s[50:51] op_sel_hi:[1,0]
	v_pk_mul_f32 v[16:17], v[106:107], s[50:51] op_sel_hi:[1,0]
	v_pk_mul_f32 v[4:5], v[110:111], s[50:51] op_sel_hi:[1,0]
	v_pk_mul_f32 v[6:7], v[112:113], s[50:51] op_sel_hi:[1,0]
	v_cvt_pk_bf16_f32 v4, v4, v5
	s_nop 0
	v_cvt_pk_bf16_f32 v5, v6, v7
	v_cvt_pk_bf16_f32 v6, v16, v17
	v_cvt_pk_bf16_f32 v7, v14, v15
	global_store_dwordx4 v[12:13], v[4:7], off offset:256 sc1
	v_pk_mul_f32 v[12:13], v[130:131], s[50:51] op_sel_hi:[1,0]
	s_nop 0
	v_or_b32_e32 v4, 48, v8
	v_ashrrev_i32_e32 v5, 31, v4
	v_lshlrev_b64 v[4:5], 13, v[4:5]
	v_lshl_add_u64 v[4:5], s[0:1], 0, v[4:5]
	v_lshl_add_u64 v[8:9], v[4:5], 0, v[10:11]
	v_pk_mul_f32 v[6:7], v[136:137], s[50:51] op_sel_hi:[1,0]
	v_pk_mul_f32 v[4:5], v[134:135], s[50:51] op_sel_hi:[1,0]
	v_pk_mul_f32 v[10:11], v[132:133], s[50:51] op_sel_hi:[1,0]
	v_cvt_pk_bf16_f32 v4, v4, v5
	v_cvt_pk_bf16_f32 v5, v6, v7
	v_cvt_pk_bf16_f32 v6, v12, v13
	v_pk_mul_f32 v[12:13], v[98:99], s[50:51] op_sel_hi:[1,0]
	v_cvt_pk_bf16_f32 v7, v10, v11
	global_store_dwordx4 v[8:9], v[4:7], off sc1
	v_pk_mul_f32 v[10:11], v[100:101], s[50:51] op_sel_hi:[1,0]
	s_nop 0
	v_pk_mul_f32 v[6:7], v[104:105], s[50:51] op_sel_hi:[1,0]
	v_pk_mul_f32 v[4:5], v[102:103], s[50:51] op_sel_hi:[1,0]
	s_nop 0
	v_cvt_pk_bf16_f32 v4, v4, v5
	v_cvt_pk_bf16_f32 v5, v6, v7
	v_cvt_pk_bf16_f32 v6, v12, v13
	v_cvt_pk_bf16_f32 v7, v10, v11
	global_store_dwordx4 v[8:9], v[4:7], off offset:256 sc1
	v_lshl_add_u64 v[8:9], v[2:3], 0, s[4:5]
	v_pk_mul_f32 v[10:11], v[92:93], s[50:51] op_sel_hi:[1,0]
	v_pk_mul_f32 v[6:7], v[96:97], s[50:51] op_sel_hi:[1,0]
	v_pk_mul_f32 v[4:5], v[94:95], s[50:51] op_sel_hi:[1,0]
	s_mov_b32 s4, 0x100000
	v_pk_mul_f32 v[12:13], v[90:91], s[50:51] op_sel_hi:[1,0]
	v_cvt_pk_bf16_f32 v4, v4, v5
	v_cvt_pk_bf16_f32 v5, v6, v7
	s_nop 0
	v_cvt_pk_bf16_f32 v6, v12, v13
	v_cvt_pk_bf16_f32 v7, v10, v11
	v_add_co_u32_e32 v10, vcc, s4, v2
	v_pk_mul_f32 v[12:13], v[58:59], s[50:51] op_sel_hi:[1,0]
	s_nop 0
	v_addc_co_u32_e32 v11, vcc, 0, v3, vcc
	global_store_dwordx4 v[10:11], v[4:7], off sc1
	v_pk_mul_f32 v[10:11], v[60:61], s[50:51] op_sel_hi:[1,0]
	s_mov_b64 s[4:5], 0x120000
	v_pk_mul_f32 v[6:7], v[64:65], s[50:51] op_sel_hi:[1,0]
	v_pk_mul_f32 v[4:5], v[62:63], s[50:51] op_sel_hi:[1,0]
	s_nop 0
	v_cvt_pk_bf16_f32 v4, v4, v5
	v_cvt_pk_bf16_f32 v5, v6, v7
	v_cvt_pk_bf16_f32 v6, v12, v13
	v_cvt_pk_bf16_f32 v7, v10, v11
	global_store_dwordx4 v[8:9], v[4:7], off offset:256 sc1
	v_lshl_add_u64 v[8:9], v[2:3], 0, s[4:5]
	v_pk_mul_f32 v[10:11], v[84:85], s[50:51] op_sel_hi:[1,0]
	v_pk_mul_f32 v[6:7], v[88:89], s[50:51] op_sel_hi:[1,0]
	v_pk_mul_f32 v[4:5], v[86:87], s[50:51] op_sel_hi:[1,0]
	s_mov_b32 s4, 0x120000
	v_pk_mul_f32 v[12:13], v[82:83], s[50:51] op_sel_hi:[1,0]
	v_cvt_pk_bf16_f32 v4, v4, v5
	v_cvt_pk_bf16_f32 v5, v6, v7
	s_nop 0
	v_cvt_pk_bf16_f32 v6, v12, v13
	v_cvt_pk_bf16_f32 v7, v10, v11
	v_add_co_u32_e32 v10, vcc, s4, v2
	v_pk_mul_f32 v[12:13], v[50:51], s[50:51] op_sel_hi:[1,0]
	s_nop 0
	v_addc_co_u32_e32 v11, vcc, 0, v3, vcc
	global_store_dwordx4 v[10:11], v[4:7], off sc1
	v_pk_mul_f32 v[10:11], v[52:53], s[50:51] op_sel_hi:[1,0]
	s_mov_b64 s[4:5], 0x140000
	v_pk_mul_f32 v[6:7], v[56:57], s[50:51] op_sel_hi:[1,0]
	v_pk_mul_f32 v[4:5], v[54:55], s[50:51] op_sel_hi:[1,0]
	s_nop 0
	v_cvt_pk_bf16_f32 v4, v4, v5
	v_cvt_pk_bf16_f32 v5, v6, v7
	v_cvt_pk_bf16_f32 v6, v12, v13
	v_cvt_pk_bf16_f32 v7, v10, v11
	global_store_dwordx4 v[8:9], v[4:7], off offset:256 sc1
	v_lshl_add_u64 v[8:9], v[2:3], 0, s[4:5]
	v_pk_mul_f32 v[10:11], v[76:77], s[50:51] op_sel_hi:[1,0]
	v_pk_mul_f32 v[6:7], v[80:81], s[50:51] op_sel_hi:[1,0]
	v_pk_mul_f32 v[4:5], v[78:79], s[50:51] op_sel_hi:[1,0]
	s_mov_b32 s4, 0x140000
	v_pk_mul_f32 v[12:13], v[74:75], s[50:51] op_sel_hi:[1,0]
	v_cvt_pk_bf16_f32 v4, v4, v5
	v_cvt_pk_bf16_f32 v5, v6, v7
	s_nop 0
	v_cvt_pk_bf16_f32 v6, v12, v13
	v_cvt_pk_bf16_f32 v7, v10, v11
	v_add_co_u32_e32 v10, vcc, s4, v2
	s_mov_b64 s[4:5], 0x160000
	s_nop 0
	v_addc_co_u32_e32 v11, vcc, 0, v3, vcc
	global_store_dwordx4 v[10:11], v[4:7], off sc1
	v_pk_mul_f32 v[10:11], v[44:45], s[50:51] op_sel_hi:[1,0]
	v_pk_mul_f32 v[12:13], v[42:43], s[50:51] op_sel_hi:[1,0]
	v_pk_mul_f32 v[6:7], v[48:49], s[50:51] op_sel_hi:[1,0]
	v_pk_mul_f32 v[4:5], v[46:47], s[50:51] op_sel_hi:[1,0]
	s_nop 0
	v_cvt_pk_bf16_f32 v4, v4, v5
	v_cvt_pk_bf16_f32 v5, v6, v7
	v_cvt_pk_bf16_f32 v6, v12, v13
	v_cvt_pk_bf16_f32 v7, v10, v11
	global_store_dwordx4 v[8:9], v[4:7], off offset:256 sc1
	v_lshl_add_u64 v[8:9], v[2:3], 0, s[4:5]
	s_mov_b32 s4, 0x160000
	v_pk_mul_f32 v[4:5], v[70:71], s[50:51] op_sel_hi:[1,0]
	v_add_co_u32_e32 v2, vcc, s4, v2
	v_pk_mul_f32 v[6:7], v[72:73], s[50:51] op_sel_hi:[1,0]
	v_cvt_pk_bf16_f32 v4, v4, v5
	s_nop 0
	v_addc_co_u32_e32 v3, vcc, 0, v3, vcc
	v_cvt_pk_bf16_f32 v5, v6, v7
	v_pk_mul_f32 v[10:11], v[68:69], s[50:51] op_sel_hi:[1,0]
	v_pk_mul_f32 v[12:13], v[66:67], s[50:51] op_sel_hi:[1,0]
	s_andn2_b64 vcc, exec, s[2:3]
	v_cvt_pk_bf16_f32 v6, v12, v13
	v_cvt_pk_bf16_f32 v7, v10, v11
	global_store_dwordx4 v[2:3], v[4:7], off sc1
	v_pk_mul_f32 v[2:3], v[38:39], s[50:51] op_sel_hi:[1,0]
	s_mov_b64 s[2:3], -1
	v_pk_mul_f32 v[4:5], v[40:41], s[50:51] op_sel_hi:[1,0]
	v_pk_mul_f32 v[6:7], v[36:37], s[50:51] op_sel_hi:[1,0]
	v_pk_mul_f32 v[10:11], v[34:35], s[50:51] op_sel_hi:[1,0]
	v_cvt_pk_bf16_f32 v2, v2, v3
	v_cvt_pk_bf16_f32 v3, v4, v5
	s_nop 0
	v_cvt_pk_bf16_f32 v4, v10, v11
	v_cvt_pk_bf16_f32 v5, v6, v7
	global_store_dwordx4 v[8:9], v[2:5], off offset:256 sc1
	s_cbranch_vccnz .LBB0_613
	s_andn2_b64 vcc, exec, s[38:39]
	s_cbranch_vccnz .LBB0_612
	s_barrier
	s_branch .LBB0_612

.LBB0_798:
	v_mov_b32_e32 v2, v179
	s_cmp_eq_u32 s85, 0
	s_nop 7
	s_nop 7
	s_nop 7
	s_cselect_b64 vcc, -1, 0
	v_add_u32_e32 v3, 0xffffe000, v2
	v_cndmask_b32_e32 v2, v3, v2, vcc
	v_lshl_add_u32 v2, s42, 8, v2
	s_and_b64 s[44:45], vcc, exec
	v_ashrrev_i32_e32 v3, 31, v2
	s_cselect_b32 s45, s21, s17
	s_cselect_b32 s44, s20, s16
	v_lshlrev_b64 v[2:3], 13, v[2:3]
	s_waitcnt vmcnt(0)
	v_pk_mul_f32 v[184:185], v[142:143], s[26:27] op_sel_hi:[1,0]
	v_lshl_add_u64 v[2:3], s[44:45], 0, v[2:3]
	v_pk_mul_f32 v[176:177], v[138:139], s[26:27] op_sel_hi:[1,0]
	v_pk_mul_f32 v[182:183], v[144:145], s[26:27] op_sel_hi:[1,0]
	v_pk_mul_f32 v[192:193], v[134:135], v[184:185]
	v_lshl_add_u64 v[6:7], v[172:173], 1, v[2:3]
	v_pk_mul_f32 v[172:173], v[150:151], s[26:27] op_sel_hi:[1,0]
	v_pk_mul_f32 v[174:175], v[140:141], s[26:27] op_sel_hi:[1,0]
	v_pk_mul_f32 v[186:187], v[136:137], v[182:183]
	v_pk_mul_f32 v[194:195], v[130:131], v[176:177]
	v_cvt_pk_bf16_f32 v192, v192, v193
	v_cvt_pk_bf16_f32 v193, v186, v187
	v_pk_mul_f32 v[4:5], v[146:147], s[26:27] op_sel_hi:[1,0]
	v_pk_mul_f32 v[8:9], v[152:153], s[26:27] op_sel_hi:[1,0]
	v_pk_mul_f32 v[196:197], v[132:133], v[174:175]
	v_cvt_pk_bf16_f32 v194, v194, v195
	v_pk_mul_f32 v[2:3], v[148:149], s[26:27] op_sel_hi:[1,0]
	v_cvt_pk_bf16_f32 v195, v196, v197
	global_store_dwordx4 v[6:7], v[192:195], off sc1
	v_pk_mul_f32 v[186:187], v[104:105], v[8:9]
	v_pk_mul_f32 v[196:197], v[100:101], v[2:3]
	v_pk_mul_f32 v[192:193], v[102:103], v[172:173]
	v_pk_mul_f32 v[194:195], v[98:99], v[4:5]
	v_cvt_pk_bf16_f32 v192, v192, v193
	v_cvt_pk_bf16_f32 v193, v186, v187
	v_pk_mul_f32 v[186:187], v[128:129], v[182:183]
	v_cvt_pk_bf16_f32 v194, v194, v195
	v_cvt_pk_bf16_f32 v195, v196, v197
	global_store_dwordx4 v[6:7], v[192:195], off offset:256 sc1
	v_pk_mul_f32 v[196:197], v[124:125], v[174:175]
	v_pk_mul_f32 v[198:199], v[90:91], v[4:5]
	v_pk_mul_f32 v[192:193], v[126:127], v[184:185]
	v_pk_mul_f32 v[194:195], v[122:123], v[176:177]
	v_cvt_pk_bf16_f32 v192, v192, v193
	v_cvt_pk_bf16_f32 v193, v186, v187
	v_add_co_u32_e32 v186, vcc, s76, v6
	v_cvt_pk_bf16_f32 v194, v194, v195
	v_cvt_pk_bf16_f32 v195, v196, v197
	v_pk_mul_f32 v[196:197], v[92:93], v[2:3]
	s_nop 0
	v_addc_co_u32_e32 v187, vcc, 0, v7, vcc
	global_store_dwordx4 v[186:187], v[192:195], off sc1
	s_nop 1
	v_pk_mul_f32 v[192:193], v[94:95], v[172:173]
	v_pk_mul_f32 v[194:195], v[96:97], v[8:9]
	v_cvt_pk_bf16_f32 v192, v192, v193
	s_nop 0
	v_cvt_pk_bf16_f32 v193, v194, v195
	v_cvt_pk_bf16_f32 v194, v198, v199
	v_cvt_pk_bf16_f32 v195, v196, v197
	global_store_dwordx4 v[186:187], v[192:195], off offset:256 sc1
	v_pk_mul_f32 v[186:187], v[120:121], v[182:183]
	v_pk_mul_f32 v[196:197], v[116:117], v[174:175]
	v_pk_mul_f32 v[192:193], v[118:119], v[184:185]
	v_pk_mul_f32 v[194:195], v[114:115], v[176:177]
	v_cvt_pk_bf16_f32 v192, v192, v193
	v_cvt_pk_bf16_f32 v193, v186, v187
	v_add_co_u32_e32 v186, vcc, s77, v6
	v_cvt_pk_bf16_f32 v194, v194, v195
	v_cvt_pk_bf16_f32 v195, v196, v197
	v_pk_mul_f32 v[196:197], v[84:85], v[2:3]
	s_nop 0
	v_addc_co_u32_e32 v187, vcc, 0, v7, vcc
	global_store_dwordx4 v[186:187], v[192:195], off sc1
	v_pk_mul_f32 v[198:199], v[82:83], v[4:5]
	s_nop 0
	v_pk_mul_f32 v[192:193], v[86:87], v[172:173]
	v_pk_mul_f32 v[194:195], v[88:89], v[8:9]
	v_cvt_pk_bf16_f32 v192, v192, v193
	s_nop 0
	v_cvt_pk_bf16_f32 v193, v194, v195
	v_cvt_pk_bf16_f32 v194, v198, v199
	v_cvt_pk_bf16_f32 v195, v196, v197
	global_store_dwordx4 v[186:187], v[192:195], off offset:256 sc1
	v_pk_mul_f32 v[186:187], v[112:113], v[182:183]
	v_pk_mul_f32 v[196:197], v[108:109], v[174:175]
	v_pk_mul_f32 v[192:193], v[110:111], v[184:185]
	v_pk_mul_f32 v[194:195], v[106:107], v[176:177]
	v_cvt_pk_bf16_f32 v192, v192, v193
	v_cvt_pk_bf16_f32 v193, v186, v187
	v_add_co_u32_e32 v186, vcc, s78, v6
	v_cvt_pk_bf16_f32 v194, v194, v195
	v_cvt_pk_bf16_f32 v195, v196, v197
	v_pk_mul_f32 v[196:197], v[76:77], v[2:3]
	s_nop 0
	v_addc_co_u32_e32 v187, vcc, 0, v7, vcc
	global_store_dwordx4 v[186:187], v[192:195], off sc1
	v_pk_mul_f32 v[198:199], v[74:75], v[4:5]
	s_nop 0
	v_pk_mul_f32 v[192:193], v[78:79], v[172:173]
	v_pk_mul_f32 v[194:195], v[80:81], v[8:9]
	v_cvt_pk_bf16_f32 v192, v192, v193
	s_nop 0
	v_cvt_pk_bf16_f32 v193, v194, v195
	v_cvt_pk_bf16_f32 v194, v198, v199
	v_cvt_pk_bf16_f32 v195, v196, v197
	global_store_dwordx4 v[186:187], v[192:195], off offset:256 sc1
	v_pk_mul_f32 v[186:187], v[72:73], v[182:183]
	v_pk_mul_f32 v[196:197], v[68:69], v[174:175]
	v_pk_mul_f32 v[192:193], v[70:71], v[184:185]
	v_pk_mul_f32 v[194:195], v[66:67], v[176:177]
	v_cvt_pk_bf16_f32 v192, v192, v193
	v_cvt_pk_bf16_f32 v193, v186, v187
	v_add_co_u32_e32 v186, vcc, s79, v6
	v_cvt_pk_bf16_f32 v194, v194, v195
	v_cvt_pk_bf16_f32 v195, v196, v197
	v_pk_mul_f32 v[196:197], v[36:37], v[2:3]
	s_nop 0
	v_addc_co_u32_e32 v187, vcc, 0, v7, vcc
	global_store_dwordx4 v[186:187], v[192:195], off sc1
	v_pk_mul_f32 v[198:199], v[34:35], v[4:5]
	s_nop 0
	v_pk_mul_f32 v[192:193], v[38:39], v[172:173]
	v_pk_mul_f32 v[194:195], v[40:41], v[8:9]
	v_cvt_pk_bf16_f32 v192, v192, v193
	s_nop 0
	v_cvt_pk_bf16_f32 v193, v194, v195
	v_cvt_pk_bf16_f32 v194, v198, v199
	v_cvt_pk_bf16_f32 v195, v196, v197
	global_store_dwordx4 v[186:187], v[192:195], off offset:256 sc1
	v_pk_mul_f32 v[186:187], v[64:65], v[182:183]
	v_pk_mul_f32 v[196:197], v[60:61], v[174:175]
	v_pk_mul_f32 v[192:193], v[62:63], v[184:185]
	v_pk_mul_f32 v[194:195], v[58:59], v[176:177]
	v_cvt_pk_bf16_f32 v192, v192, v193
	v_cvt_pk_bf16_f32 v193, v186, v187
	v_add_co_u32_e32 v186, vcc, s80, v6
	v_cvt_pk_bf16_f32 v194, v194, v195
	v_cvt_pk_bf16_f32 v195, v196, v197
	v_pk_mul_f32 v[196:197], v[28:29], v[2:3]
	s_nop 0
	v_addc_co_u32_e32 v187, vcc, 0, v7, vcc
	global_store_dwordx4 v[186:187], v[192:195], off sc1
	v_pk_mul_f32 v[198:199], v[26:27], v[4:5]
	s_nop 0
	v_pk_mul_f32 v[192:193], v[30:31], v[172:173]
	v_pk_mul_f32 v[194:195], v[32:33], v[8:9]
	v_cvt_pk_bf16_f32 v192, v192, v193
	s_nop 0
	v_cvt_pk_bf16_f32 v193, v194, v195
	v_cvt_pk_bf16_f32 v194, v198, v199
	v_cvt_pk_bf16_f32 v195, v196, v197
	global_store_dwordx4 v[186:187], v[192:195], off offset:256 sc1
	v_pk_mul_f32 v[186:187], v[56:57], v[182:183]
	v_pk_mul_f32 v[196:197], v[52:53], v[174:175]
	v_pk_mul_f32 v[192:193], v[54:55], v[184:185]
	v_pk_mul_f32 v[194:195], v[50:51], v[176:177]
	v_cvt_pk_bf16_f32 v192, v192, v193
	v_cvt_pk_bf16_f32 v193, v186, v187
	v_add_co_u32_e32 v186, vcc, s81, v6
	v_cvt_pk_bf16_f32 v194, v194, v195
	v_cvt_pk_bf16_f32 v195, v196, v197
	v_pk_mul_f32 v[196:197], v[20:21], v[2:3]
	s_nop 0
	v_addc_co_u32_e32 v187, vcc, 0, v7, vcc
	v_add_co_u32_e32 v6, vcc, s82, v6
	global_store_dwordx4 v[186:187], v[192:195], off sc1
	s_nop 0
	v_addc_co_u32_e32 v7, vcc, 0, v7, vcc
	v_pk_mul_f32 v[194:195], v[24:25], v[8:9]
	v_pk_mul_f32 v[192:193], v[22:23], v[172:173]
	v_pk_mul_f32 v[198:199], v[18:19], v[4:5]
	v_cvt_pk_bf16_f32 v192, v192, v193
	v_cvt_pk_bf16_f32 v193, v194, v195
	v_pk_mul_f32 v[182:183], v[48:49], v[182:183]
	v_cvt_pk_bf16_f32 v194, v198, v199
	v_cvt_pk_bf16_f32 v195, v196, v197
	global_store_dwordx4 v[186:187], v[192:195], off offset:256 sc1
	v_pk_mul_f32 v[184:185], v[46:47], v[184:185]
	v_pk_mul_f32 v[186:187], v[44:45], v[174:175]
	v_pk_mul_f32 v[176:177], v[42:43], v[176:177]
	v_cvt_pk_bf16_f32 v174, v184, v185
	v_cvt_pk_bf16_f32 v175, v182, v183
	v_pk_mul_f32 v[4:5], v[10:11], v[4:5]
	s_and_b64 vcc, exec, s[2:3]
	s_mov_b64 s[2:3], -1
	v_cvt_pk_bf16_f32 v176, v176, v177
	v_cvt_pk_bf16_f32 v177, v186, v187
	global_store_dwordx4 v[6:7], v[174:177], off sc1
	v_pk_mul_f32 v[8:9], v[16:17], v[8:9]
	v_pk_mul_f32 v[172:173], v[14:15], v[172:173]
	v_pk_mul_f32 v[174:175], v[12:13], v[2:3]
	v_cvt_pk_bf16_f32 v2, v172, v173
	v_cvt_pk_bf16_f32 v3, v8, v9
	v_cvt_pk_bf16_f32 v4, v4, v5
	s_nop 0
	v_cvt_pk_bf16_f32 v5, v174, v175
	global_store_dwordx4 v[6:7], v[2:5], off offset:256 sc1
	s_cbranch_vccnz .LBB0_778
	s_andn2_b64 vcc, exec, s[6:7]
	s_cbranch_vccnz .LBB0_777
	s_barrier
	s_branch .LBB0_777

.LBB0_1038:
	v_mov_b32_e32 v2, v179
	s_cmp_eq_u32 s81, 0
	s_nop 7
	s_nop 7
	s_nop 7
	s_cselect_b64 vcc, -1, 0
	v_add_u32_e32 v3, 0xffffe000, v2
	v_cndmask_b32_e32 v2, v3, v2, vcc
	v_lshl_add_u32 v2, s80, 8, v2
	s_and_b64 s[26:27], vcc, exec
	v_ashrrev_i32_e32 v3, 31, v2
	s_cselect_b32 s27, s21, s17
	s_cselect_b32 s26, s20, s16
	v_lshlrev_b64 v[2:3], 13, v[2:3]
	s_waitcnt vmcnt(0)
	v_pk_mul_f32 v[184:185], v[142:143], s[22:23] op_sel_hi:[1,0]
	v_lshl_add_u64 v[2:3], s[26:27], 0, v[2:3]
	v_pk_mul_f32 v[176:177], v[138:139], s[22:23] op_sel_hi:[1,0]
	v_pk_mul_f32 v[182:183], v[144:145], s[22:23] op_sel_hi:[1,0]
	v_pk_mul_f32 v[192:193], v[134:135], v[184:185]
	v_lshl_add_u64 v[6:7], v[172:173], 1, v[2:3]
	v_pk_mul_f32 v[172:173], v[150:151], s[22:23] op_sel_hi:[1,0]
	v_pk_mul_f32 v[174:175], v[140:141], s[22:23] op_sel_hi:[1,0]
	v_pk_mul_f32 v[186:187], v[136:137], v[182:183]
	v_pk_mul_f32 v[194:195], v[130:131], v[176:177]
	v_cvt_pk_bf16_f32 v192, v192, v193
	v_cvt_pk_bf16_f32 v193, v186, v187
	v_pk_mul_f32 v[4:5], v[146:147], s[22:23] op_sel_hi:[1,0]
	v_pk_mul_f32 v[8:9], v[152:153], s[22:23] op_sel_hi:[1,0]
	v_pk_mul_f32 v[196:197], v[132:133], v[174:175]
	v_cvt_pk_bf16_f32 v194, v194, v195
	v_pk_mul_f32 v[2:3], v[148:149], s[22:23] op_sel_hi:[1,0]
	v_cvt_pk_bf16_f32 v195, v196, v197
	global_store_dwordx4 v[6:7], v[192:195], off sc1
	v_pk_mul_f32 v[186:187], v[104:105], v[8:9]
	v_pk_mul_f32 v[196:197], v[100:101], v[2:3]
	v_pk_mul_f32 v[192:193], v[102:103], v[172:173]
	v_pk_mul_f32 v[194:195], v[98:99], v[4:5]
	v_cvt_pk_bf16_f32 v192, v192, v193
	v_cvt_pk_bf16_f32 v193, v186, v187
	v_pk_mul_f32 v[186:187], v[128:129], v[182:183]
	v_cvt_pk_bf16_f32 v194, v194, v195
	v_cvt_pk_bf16_f32 v195, v196, v197
	global_store_dwordx4 v[6:7], v[192:195], off offset:256 sc1
	v_pk_mul_f32 v[196:197], v[124:125], v[174:175]
	v_pk_mul_f32 v[198:199], v[90:91], v[4:5]
	v_pk_mul_f32 v[192:193], v[126:127], v[184:185]
	v_pk_mul_f32 v[194:195], v[122:123], v[176:177]
	v_cvt_pk_bf16_f32 v192, v192, v193
	v_cvt_pk_bf16_f32 v193, v186, v187
	v_add_co_u32_e32 v186, vcc, s61, v6
	v_cvt_pk_bf16_f32 v194, v194, v195
	v_cvt_pk_bf16_f32 v195, v196, v197
	v_pk_mul_f32 v[196:197], v[92:93], v[2:3]
	s_nop 0
	v_addc_co_u32_e32 v187, vcc, 0, v7, vcc
	global_store_dwordx4 v[186:187], v[192:195], off sc1
	s_nop 1
	v_pk_mul_f32 v[192:193], v[94:95], v[172:173]
	v_pk_mul_f32 v[194:195], v[96:97], v[8:9]
	v_cvt_pk_bf16_f32 v192, v192, v193
	s_nop 0
	v_cvt_pk_bf16_f32 v193, v194, v195
	v_cvt_pk_bf16_f32 v194, v198, v199
	v_cvt_pk_bf16_f32 v195, v196, v197
	global_store_dwordx4 v[186:187], v[192:195], off offset:256 sc1
	v_pk_mul_f32 v[186:187], v[120:121], v[182:183]
	v_pk_mul_f32 v[196:197], v[116:117], v[174:175]
	v_pk_mul_f32 v[192:193], v[118:119], v[184:185]
	v_pk_mul_f32 v[194:195], v[114:115], v[176:177]
	v_cvt_pk_bf16_f32 v192, v192, v193
	v_cvt_pk_bf16_f32 v193, v186, v187
	v_add_co_u32_e32 v186, vcc, s68, v6
	v_cvt_pk_bf16_f32 v194, v194, v195
	v_cvt_pk_bf16_f32 v195, v196, v197
	v_pk_mul_f32 v[196:197], v[84:85], v[2:3]
	s_nop 0
	v_addc_co_u32_e32 v187, vcc, 0, v7, vcc
	global_store_dwordx4 v[186:187], v[192:195], off sc1
	v_pk_mul_f32 v[198:199], v[82:83], v[4:5]
	s_nop 0
	v_pk_mul_f32 v[192:193], v[86:87], v[172:173]
	v_pk_mul_f32 v[194:195], v[88:89], v[8:9]
	v_cvt_pk_bf16_f32 v192, v192, v193
	s_nop 0
	v_cvt_pk_bf16_f32 v193, v194, v195
	v_cvt_pk_bf16_f32 v194, v198, v199
	v_cvt_pk_bf16_f32 v195, v196, v197
	global_store_dwordx4 v[186:187], v[192:195], off offset:256 sc1
	v_pk_mul_f32 v[186:187], v[112:113], v[182:183]
	v_pk_mul_f32 v[196:197], v[108:109], v[174:175]
	v_pk_mul_f32 v[192:193], v[110:111], v[184:185]
	v_pk_mul_f32 v[194:195], v[106:107], v[176:177]
	v_cvt_pk_bf16_f32 v192, v192, v193
	v_cvt_pk_bf16_f32 v193, v186, v187
	v_add_co_u32_e32 v186, vcc, s69, v6
	v_cvt_pk_bf16_f32 v194, v194, v195
	v_cvt_pk_bf16_f32 v195, v196, v197
	v_pk_mul_f32 v[196:197], v[76:77], v[2:3]
	s_nop 0
	v_addc_co_u32_e32 v187, vcc, 0, v7, vcc
	global_store_dwordx4 v[186:187], v[192:195], off sc1
	v_pk_mul_f32 v[198:199], v[74:75], v[4:5]
	s_nop 0
	v_pk_mul_f32 v[192:193], v[78:79], v[172:173]
	v_pk_mul_f32 v[194:195], v[80:81], v[8:9]
	v_cvt_pk_bf16_f32 v192, v192, v193
	s_nop 0
	v_cvt_pk_bf16_f32 v193, v194, v195
	v_cvt_pk_bf16_f32 v194, v198, v199
	v_cvt_pk_bf16_f32 v195, v196, v197
	global_store_dwordx4 v[186:187], v[192:195], off offset:256 sc1
	v_pk_mul_f32 v[186:187], v[72:73], v[182:183]
	v_pk_mul_f32 v[196:197], v[68:69], v[174:175]
	v_pk_mul_f32 v[192:193], v[70:71], v[184:185]
	v_pk_mul_f32 v[194:195], v[66:67], v[176:177]
	v_cvt_pk_bf16_f32 v192, v192, v193
	v_cvt_pk_bf16_f32 v193, v186, v187
	v_add_co_u32_e32 v186, vcc, s72, v6
	v_cvt_pk_bf16_f32 v194, v194, v195
	v_cvt_pk_bf16_f32 v195, v196, v197
	v_pk_mul_f32 v[196:197], v[36:37], v[2:3]
	s_nop 0
	v_addc_co_u32_e32 v187, vcc, 0, v7, vcc
	global_store_dwordx4 v[186:187], v[192:195], off sc1
	v_pk_mul_f32 v[198:199], v[34:35], v[4:5]
	s_nop 0
	v_pk_mul_f32 v[192:193], v[38:39], v[172:173]
	v_pk_mul_f32 v[194:195], v[40:41], v[8:9]
	v_cvt_pk_bf16_f32 v192, v192, v193
	s_nop 0
	v_cvt_pk_bf16_f32 v193, v194, v195
	v_cvt_pk_bf16_f32 v194, v198, v199
	v_cvt_pk_bf16_f32 v195, v196, v197
	global_store_dwordx4 v[186:187], v[192:195], off offset:256 sc1
	v_pk_mul_f32 v[186:187], v[64:65], v[182:183]
	v_pk_mul_f32 v[196:197], v[60:61], v[174:175]
	v_pk_mul_f32 v[192:193], v[62:63], v[184:185]
	v_pk_mul_f32 v[194:195], v[58:59], v[176:177]
	v_cvt_pk_bf16_f32 v192, v192, v193
	v_cvt_pk_bf16_f32 v193, v186, v187
	v_add_co_u32_e32 v186, vcc, s73, v6
	v_cvt_pk_bf16_f32 v194, v194, v195
	v_cvt_pk_bf16_f32 v195, v196, v197
	v_pk_mul_f32 v[196:197], v[28:29], v[2:3]
	s_nop 0
	v_addc_co_u32_e32 v187, vcc, 0, v7, vcc
	global_store_dwordx4 v[186:187], v[192:195], off sc1
	v_pk_mul_f32 v[198:199], v[26:27], v[4:5]
	s_nop 0
	v_pk_mul_f32 v[192:193], v[30:31], v[172:173]
	v_pk_mul_f32 v[194:195], v[32:33], v[8:9]
	v_cvt_pk_bf16_f32 v192, v192, v193
	s_nop 0
	v_cvt_pk_bf16_f32 v193, v194, v195
	v_cvt_pk_bf16_f32 v194, v198, v199
	v_cvt_pk_bf16_f32 v195, v196, v197
	global_store_dwordx4 v[186:187], v[192:195], off offset:256 sc1
	v_pk_mul_f32 v[186:187], v[56:57], v[182:183]
	v_pk_mul_f32 v[196:197], v[52:53], v[174:175]
	v_pk_mul_f32 v[192:193], v[54:55], v[184:185]
	v_pk_mul_f32 v[194:195], v[50:51], v[176:177]
	v_cvt_pk_bf16_f32 v192, v192, v193
	v_cvt_pk_bf16_f32 v193, v186, v187
	v_add_co_u32_e32 v186, vcc, s74, v6
	v_cvt_pk_bf16_f32 v194, v194, v195
	v_cvt_pk_bf16_f32 v195, v196, v197
	v_pk_mul_f32 v[196:197], v[20:21], v[2:3]
	s_nop 0
	v_addc_co_u32_e32 v187, vcc, 0, v7, vcc
	v_add_co_u32_e32 v6, vcc, s75, v6
	global_store_dwordx4 v[186:187], v[192:195], off sc1
	s_nop 0
	v_addc_co_u32_e32 v7, vcc, 0, v7, vcc
	v_pk_mul_f32 v[194:195], v[24:25], v[8:9]
	v_pk_mul_f32 v[192:193], v[22:23], v[172:173]
	v_pk_mul_f32 v[198:199], v[18:19], v[4:5]
	v_cvt_pk_bf16_f32 v192, v192, v193
	v_cvt_pk_bf16_f32 v193, v194, v195
	v_pk_mul_f32 v[182:183], v[48:49], v[182:183]
	v_cvt_pk_bf16_f32 v194, v198, v199
	v_cvt_pk_bf16_f32 v195, v196, v197
	global_store_dwordx4 v[186:187], v[192:195], off offset:256 sc1
	v_pk_mul_f32 v[184:185], v[46:47], v[184:185]
	v_pk_mul_f32 v[186:187], v[44:45], v[174:175]
	v_pk_mul_f32 v[176:177], v[42:43], v[176:177]
	v_cvt_pk_bf16_f32 v174, v184, v185
	v_cvt_pk_bf16_f32 v175, v182, v183
	v_pk_mul_f32 v[4:5], v[10:11], v[4:5]
	s_and_b64 vcc, exec, s[2:3]
	s_mov_b64 s[2:3], -1
	v_cvt_pk_bf16_f32 v176, v176, v177
	v_cvt_pk_bf16_f32 v177, v186, v187
	global_store_dwordx4 v[6:7], v[174:177], off sc1
	v_pk_mul_f32 v[8:9], v[16:17], v[8:9]
	v_pk_mul_f32 v[172:173], v[14:15], v[172:173]
	v_pk_mul_f32 v[174:175], v[12:13], v[2:3]
	v_cvt_pk_bf16_f32 v2, v172, v173
	v_cvt_pk_bf16_f32 v3, v8, v9
	v_cvt_pk_bf16_f32 v4, v4, v5
	s_nop 0
	v_cvt_pk_bf16_f32 v5, v174, v175
	global_store_dwordx4 v[6:7], v[2:5], off offset:256 sc1
	s_cbranch_vccnz .LBB0_1018
	s_andn2_b64 vcc, exec, s[6:7]
	s_cbranch_vccnz .LBB0_1017
	s_barrier
	s_branch .LBB0_1017
